# v59 with the P8 wave renumbering applied only on the 256-workgroup grid (falls back to the baseline numbering on any other grid size)
# baseline (speedup 1.0000x reference)
; #define LAS __attribute__((address_space(3)))
; __global__ void __launch_bounds__(NTHR, 2) mk_fwd(Args args) {
;     ...
;         if (gw < NGW - BS) for (int t = gw; t < T; t += NGW - BS) dsa_post_row(KRAW, KIRAW, b_k_norm, b_ki_norm, out + O_KP, out + O_KIP, KB, KIB, VB, (unsigned char*)(AP->ws + WS_K8), (unsigned char*)(AP->ws + WS_V8), t, lane);
;         for (int b = NGW - 1 - gw; b < BS; b += NGW) topk_dispatch(SCS + (size_t)b * SCS_LD, PAST + 1, IDXS + b * TOPK, (LAS unsigned*)(lds + wave * 8192), lane);
.LBB0_995:
	s_cmp_lt_i32 s26, 9
	s_cselect_b64 s[4:5], -1, 0
	s_cmp_gt_i32 s27, 8
	s_cselect_b64 s[6:7], -1, 0
	s_and_b64 s[4:5], s[4:5], s[6:7]
	s_andn2_b64 vcc, exec, s[4:5]
	s_cbranch_vccnz .LBB0_1495
	s_mul_i32 s4, s2, 7
	s_add_i32 s4, s4, s96
	s_add_i32 s5, s2, 0x700
	s_cmp_eq_u32 s96, 7
	s_cselect_b32 s4, s5, s4
	s_cmpk_eq_u32 s28, 0x100
	s_cselect_b32 s20, s4, s20
	s_add_i32 s14, s36, 0xffffff80
	s_cmp_ge_i32 s20, s14
	s_cselect_b64 s[4:5], -1, 0
	s_cmpk_gt_i32 s20, 0x1fff
	s_cselect_b64 s[6:7], -1, 0
	s_or_b64 s[4:5], s[4:5], s[6:7]
	s_mov_b64 s[12:13], s[0:1]
	s_and_b64 vcc, exec, s[4:5]
	v_mbcnt_lo_u32_b32 v0, -1, 0
	v_mbcnt_hi_u32_b32 v0, -1, v0
	s_cbranch_vccnz .LBB0_999
	s_waitcnt lgkmcnt(0)
	v_mbcnt_lo_u32_b32 v1, -1, 0
	v_mbcnt_hi_u32_b32 v4, -1, v1
	v_and_b32_e32 v1, 64, v4
	v_add_u32_e32 v5, 64, v1
	v_xor_b32_e32 v1, 1, v4
	v_cmp_lt_i32_e32 vcc, v1, v5
	v_xor_b32_e32 v2, 2, v4
	s_load_dwordx4 s[4:7], s[12:13], 0xa8
	s_load_dwordx4 s[8:11], s[12:13], 0x80
	v_cndmask_b32_e32 v1, v4, v1, vcc
	v_cmp_lt_i32_e32 vcc, v2, v5
	s_waitcnt vmcnt(0)
	v_xor_b32_e32 v8, 16, v4
	s_waitcnt lgkmcnt(0)
	s_add_u32 s16, s4, 0xe200000
	v_cndmask_b32_e32 v2, v4, v2, vcc
	v_lshlrev_b32_e32 v16, 2, v2
	v_xor_b32_e32 v2, 4, v4
	v_cmp_lt_i32_e32 vcc, v2, v5
	v_lshlrev_b32_e32 v6, 1, v0
	v_lshlrev_b32_e32 v14, 3, v0
	v_cndmask_b32_e32 v2, v4, v2, vcc
	v_lshlrev_b32_e32 v17, 2, v2
	v_xor_b32_e32 v2, 8, v4
	v_cmp_lt_i32_e32 vcc, v2, v5
	s_addc_u32 s17, s5, 0
	v_mov_b32_e32 v3, 0
	v_cndmask_b32_e32 v2, v4, v2, vcc
	v_cmp_lt_i32_e32 vcc, v8, v5
	v_lshlrev_b32_e32 v18, 2, v2
	v_lshlrev_b32_e32 v2, 5, v0
	v_cndmask_b32_e32 v8, v4, v8, vcc
	v_lshlrev_b32_e32 v19, 2, v8
	v_xor_b32_e32 v8, 32, v4
	v_and_b32_e32 v2, 0x1e0, v2
	v_ashrrev_i32_e32 v7, 31, v6
	v_cmp_lt_i32_e32 vcc, v8, v5
	s_ashr_i32 s21, s20, 31
	v_ashrrev_i32_e32 v15, 31, v14
	v_lshl_add_u64 v[2:3], s[8:9], 0, v[2:3]
	v_cndmask_b32_e32 v4, v4, v8, vcc
	v_lshlrev_b64 v[8:9], 2, v[6:7]
	s_lshl_b64 s[8:9], s[20:21], 8
	s_lshl_b64 s[18:19], s[20:21], 9
	v_lshlrev_b32_e32 v20, 2, v4
	v_lshl_add_u64 v[4:5], s[10:11], 0, v[8:9]
	v_lshl_add_u64 v[6:7], v[6:7], 1, s[8:9]
	s_mov_b64 s[8:9], 0x3bc00000
	s_ashr_i32 s15, s14, 31
	v_lshl_add_u64 v[8:9], s[18:19], 0, v[8:9]
	v_lshl_add_u64 v[10:11], s[18:19], 0, v[14:15]
	v_lshrrev_b32_e32 v64, 7, v14
	v_and_b32_e32 v65, 0x78, v14
	v_lshl_or_b32 v64, v64, 20, v65
	s_lshl_b32 s100, s20, 7
	v_add_u32_e32 v64, s100, v64
	v_mov_b32_e32 v65, 0
	s_lshl_b32 s101, s14, 7
	s_lshl_b64 s[18:19], s[20:21], 10
	s_lshl_b64 s[22:23], s[20:21], 11
	v_lshlrev_b32_e32 v1, 2, v1
	v_lshl_add_u64 v[6:7], v[6:7], 0, s[8:9]
	s_lshl_b64 s[8:9], s[14:15], 8
	s_lshl_b64 s[10:11], s[14:15], 9
	v_lshl_add_u64 v[12:13], v[14:15], 1, s[18:19]
	s_lshl_b64 s[18:19], s[14:15], 10
	v_lshl_add_u64 v[14:15], v[14:15], 2, s[22:23]
	s_lshl_b64 s[22:23], s[14:15], 11
	s_mov_b64 s[38:39], 0x39600000
	v_mov_b32_e32 v21, 0x358637bd
	s_mov_b32 s3, 0x800000
	s_mov_b32 s15, 0xc200000
	s_mov_b32 s21, 0x3ac00000
	s_mov_b32 s29, 0x4fc00000
	s_mov_b32 s30, 0x3b400000
	s_brev_b32 s31, 10
	s_mov_b32 s34, 0x3a600000
	s_mov_b32 s35, s20
